# sample-attn QK all 3 rows unified: Q hoisted, 12-slot K ring, v_pk_fma_f32 pair accumulators
# speedup vs baseline: 1.0007x; 1.0007x over previous
.LBB0_754:
	s_or_b64 exec, exec, s[10:11]
	s_bitset1_b32 s4, 14
	s_ashr_i32 s10, s16, 6
	s_mul_i32 s12, s4, 0x600
	s_mul_hi_u32 s11, s4, 0x600
	s_add_u32 s12, s26, s12
	s_addc_u32 s13, s27, s11
	v_lshl_add_u64 v[0:1], v[8:9], 1, s[12:13]
	s_mov_b32 s11, 0x6a80000
	v_add_co_u32_e32 v0, vcc, s11, v0
	v_readlane_b32 s17, v255, 53
	s_nop 0
	v_addc_co_u32_e32 v1, vcc, 0, v1, vcc
	v_lshl_add_u32 v1, v8, 2, s17
	s_add_i32 s11, s10, 1
	v_and_b32_e32 v64, 63, v8
	v_mov_b32_e32 v0, v209
	v_lshlrev_b32_e32 v0, 16, v0
	ds_write_b32 v1, v0
	v_cvt_f32_i32_e32 v0, s11
	s_mov_b32 s11, 0x42fc0000
	s_waitcnt lgkmcnt(0)
	s_barrier
	v_cmp_lt_f32_e32 vcc, s11, v0
	s_and_b64 s[12:13], vcc, exec
	s_cselect_b32 s11, 0xffffffc0, 0
	v_cndmask_b32_e32 v1, 0, v242, vcc
	s_add_i32 s12, s10, s58
	v_sub_f32_e32 v0, v1, v0
	s_ashr_i32 s13, s12, 31
	v_exp_f32_e32 v0, v0
	s_lshl_b64 s[12:13], s[12:13], 2
	s_add_u32 s12, s22, s12
	s_addc_u32 s13, s23, s13
	global_load_dword v65, v175, s[12:13]
	s_and_b32 s12, s16, 0xffffff00
	s_and_b32 s24, s16, 0xffffffc0
	v_ldexp_f32 v0, v0, s11
	s_add_i32 s11, s12, 0
	s_lshl_b32 s13, s24, 2
	s_add_i32 s13, s17, s13
	v_mul_f32_e32 v66, 0x3fb8aa3b, v0
	v_mov_b32_e32 v0, s11
	v_mad_u32_u24 v67, v64, s72, v0
	v_mov_b32_e32 v44, s13
	ds_read_b128 v[28:31], v44
	ds_read_b128 v[8:11], v44 offset:16
	ds_read_b128 v[4:7], v44 offset:32
	ds_read_b128 v[0:3], v44 offset:48
	ds_read_b128 v[24:27], v44 offset:64
	ds_read_b128 v[16:19], v44 offset:80
	ds_read_b128 v[20:23], v44 offset:96
	ds_read_b128 v[12:15], v44 offset:112
	ds_read_b128 v[48:51], v44 offset:128
	ds_read_b128 v[32:35], v44 offset:144
	ds_read_b128 v[52:55], v44 offset:160
	ds_read_b128 v[36:39], v44 offset:176
	ds_read_b128 v[56:59], v44 offset:192
	ds_read_b128 v[40:43], v44 offset:208
	ds_read_b128 v[60:63], v44 offset:224
	ds_read_b128 v[44:47], v44 offset:240
	s_add_i32 s13, s11, 0x10800
	v_mov_b32_e32 v184, s13
	v_cmp_eq_u32_e32 vcc, 0, v64
	ds_read_b128 v[116:119], v67
	ds_read_b128 v[120:123], v67 offset:16
	ds_read_b128 v[124:127], v67 offset:32
	ds_read_b128 v[128:131], v67 offset:48
	ds_read_b128 v[132:135], v67 offset:64
	ds_read_b128 v[136:139], v67 offset:80
	ds_read_b128 v[140:143], v67 offset:96
	ds_read_b128 v[144:147], v67 offset:112
	ds_read_b128 v[148:151], v67 offset:128
	ds_read_b128 v[152:155], v67 offset:144
	ds_read_b128 v[156:159], v67 offset:160
	ds_read_b128 v[160:163], v67 offset:176
	v_sub_u32_e32 v69, 0x80, v64
	v_cvt_f32_ubyte0_e32 v69, v69
	v_or_b32_e32 v70, 64, v64
	v_sub_u32_e32 v70, 0x80, v70
	v_cvt_f32_ubyte0_e32 v70, v70
	s_waitcnt lgkmcnt(11)
	v_pk_mul_f32 v[186:187], v[28:29], v[116:117]
	v_pk_mul_f32 v[188:189], v[30:31], v[118:119]
	ds_read_b128 v[116:119], v67 offset:192
	s_waitcnt lgkmcnt(11)
	v_pk_fma_f32 v[186:187], v[8:9], v[120:121], v[186:187]
	v_pk_fma_f32 v[188:189], v[10:11], v[122:123], v[188:189]
	ds_read_b128 v[120:123], v67 offset:208
	s_waitcnt lgkmcnt(11)
	v_pk_fma_f32 v[186:187], v[4:5], v[124:125], v[186:187]
	v_pk_fma_f32 v[188:189], v[6:7], v[126:127], v[188:189]
	ds_read_b128 v[124:127], v67 offset:224
	s_waitcnt lgkmcnt(11)
	v_pk_fma_f32 v[186:187], v[0:1], v[128:129], v[186:187]
	v_pk_fma_f32 v[188:189], v[2:3], v[130:131], v[188:189]
	ds_read_b128 v[128:131], v67 offset:240
	s_waitcnt lgkmcnt(11)
	v_pk_fma_f32 v[186:187], v[24:25], v[132:133], v[186:187]
	v_pk_fma_f32 v[188:189], v[26:27], v[134:135], v[188:189]
	ds_read_b128 v[132:135], v67 offset:33792
	s_waitcnt lgkmcnt(11)
	v_pk_fma_f32 v[186:187], v[16:17], v[136:137], v[186:187]
	v_pk_fma_f32 v[188:189], v[18:19], v[138:139], v[188:189]
	ds_read_b128 v[136:139], v67 offset:33808
	s_waitcnt lgkmcnt(11)
	v_pk_fma_f32 v[186:187], v[20:21], v[140:141], v[186:187]
	v_pk_fma_f32 v[188:189], v[22:23], v[142:143], v[188:189]
	ds_read_b128 v[140:143], v67 offset:33824
	s_waitcnt lgkmcnt(11)
	v_pk_fma_f32 v[186:187], v[12:13], v[144:145], v[186:187]
	v_pk_fma_f32 v[188:189], v[14:15], v[146:147], v[188:189]
	ds_read_b128 v[144:147], v67 offset:33840
	s_waitcnt lgkmcnt(11)
	v_pk_fma_f32 v[186:187], v[48:49], v[148:149], v[186:187]
	v_pk_fma_f32 v[188:189], v[50:51], v[150:151], v[188:189]
	ds_read_b128 v[148:151], v67 offset:33856
	s_waitcnt lgkmcnt(11)
	v_pk_fma_f32 v[186:187], v[32:33], v[152:153], v[186:187]
	v_pk_fma_f32 v[188:189], v[34:35], v[154:155], v[188:189]
	ds_read_b128 v[152:155], v67 offset:33872
	s_waitcnt lgkmcnt(11)
	v_pk_fma_f32 v[186:187], v[52:53], v[156:157], v[186:187]
	v_pk_fma_f32 v[188:189], v[54:55], v[158:159], v[188:189]
	ds_read_b128 v[156:159], v67 offset:33888
	s_waitcnt lgkmcnt(11)
	v_pk_fma_f32 v[186:187], v[36:37], v[160:161], v[186:187]
	v_pk_fma_f32 v[188:189], v[38:39], v[162:163], v[188:189]
	ds_read_b128 v[160:163], v67 offset:33904
	s_waitcnt lgkmcnt(11)
	v_pk_fma_f32 v[186:187], v[56:57], v[116:117], v[186:187]
	v_pk_fma_f32 v[188:189], v[58:59], v[118:119], v[188:189]
	ds_read_b128 v[116:119], v67 offset:33920
	s_waitcnt lgkmcnt(11)
	v_pk_fma_f32 v[186:187], v[40:41], v[120:121], v[186:187]
	v_pk_fma_f32 v[188:189], v[42:43], v[122:123], v[188:189]
	ds_read_b128 v[120:123], v67 offset:33936
	s_waitcnt lgkmcnt(11)
	v_pk_fma_f32 v[186:187], v[60:61], v[124:125], v[186:187]
	v_pk_fma_f32 v[188:189], v[62:63], v[126:127], v[188:189]
	ds_read_b128 v[124:127], v67 offset:33952
	s_waitcnt lgkmcnt(11)
	v_pk_fma_f32 v[186:187], v[44:45], v[128:129], v[186:187]
	v_pk_fma_f32 v[188:189], v[46:47], v[130:131], v[188:189]
	ds_read_b128 v[128:131], v67 offset:33968
	s_waitcnt lgkmcnt(11)
	v_pk_mul_f32 v[190:191], v[28:29], v[132:133]
	v_pk_mul_f32 v[192:193], v[30:31], v[134:135]
	ds_read_b128 v[132:135], v67 offset:33984
	s_waitcnt lgkmcnt(11)
	v_pk_fma_f32 v[190:191], v[8:9], v[136:137], v[190:191]
	v_pk_fma_f32 v[192:193], v[10:11], v[138:139], v[192:193]
	ds_read_b128 v[136:139], v67 offset:34000
	s_waitcnt lgkmcnt(11)
	v_pk_fma_f32 v[190:191], v[4:5], v[140:141], v[190:191]
	v_pk_fma_f32 v[192:193], v[6:7], v[142:143], v[192:193]
	ds_read_b128 v[140:143], v67 offset:34016
	s_waitcnt lgkmcnt(11)
	v_pk_fma_f32 v[190:191], v[0:1], v[144:145], v[190:191]
	v_pk_fma_f32 v[192:193], v[2:3], v[146:147], v[192:193]
	ds_read_b128 v[144:147], v67 offset:34032
	s_waitcnt lgkmcnt(11)
	v_pk_fma_f32 v[190:191], v[24:25], v[148:149], v[190:191]
	v_pk_fma_f32 v[192:193], v[26:27], v[150:151], v[192:193]
	ds_read_b128 v[148:151], v184
	s_waitcnt lgkmcnt(11)
	v_pk_fma_f32 v[190:191], v[16:17], v[152:153], v[190:191]
	v_pk_fma_f32 v[192:193], v[18:19], v[154:155], v[192:193]
	ds_read_b128 v[152:155], v184 offset:16
	s_waitcnt lgkmcnt(11)
	v_pk_fma_f32 v[190:191], v[20:21], v[156:157], v[190:191]
	v_pk_fma_f32 v[192:193], v[22:23], v[158:159], v[192:193]
	ds_read_b128 v[156:159], v184 offset:32
	s_waitcnt lgkmcnt(11)
	v_pk_fma_f32 v[190:191], v[12:13], v[160:161], v[190:191]
	v_pk_fma_f32 v[192:193], v[14:15], v[162:163], v[192:193]
	ds_read_b128 v[160:163], v184 offset:48
	s_waitcnt lgkmcnt(11)
	v_pk_fma_f32 v[190:191], v[48:49], v[116:117], v[190:191]
	v_pk_fma_f32 v[192:193], v[50:51], v[118:119], v[192:193]
	ds_read_b128 v[116:119], v184 offset:64
	s_waitcnt lgkmcnt(11)
	v_pk_fma_f32 v[190:191], v[32:33], v[120:121], v[190:191]
	v_pk_fma_f32 v[192:193], v[34:35], v[122:123], v[192:193]
	ds_read_b128 v[120:123], v184 offset:80
	s_waitcnt lgkmcnt(11)
	v_pk_fma_f32 v[190:191], v[52:53], v[124:125], v[190:191]
	v_pk_fma_f32 v[192:193], v[54:55], v[126:127], v[192:193]
	ds_read_b128 v[124:127], v184 offset:96
	s_waitcnt lgkmcnt(11)
	v_pk_fma_f32 v[190:191], v[36:37], v[128:129], v[190:191]
	v_pk_fma_f32 v[192:193], v[38:39], v[130:131], v[192:193]
	ds_read_b128 v[128:131], v184 offset:112
	s_waitcnt lgkmcnt(11)
	v_pk_fma_f32 v[190:191], v[56:57], v[132:133], v[190:191]
	v_pk_fma_f32 v[192:193], v[58:59], v[134:135], v[192:193]
	ds_read_b128 v[132:135], v184 offset:128
	s_waitcnt lgkmcnt(11)
	v_pk_fma_f32 v[190:191], v[40:41], v[136:137], v[190:191]
	v_pk_fma_f32 v[192:193], v[42:43], v[138:139], v[192:193]
	ds_read_b128 v[136:139], v184 offset:144
	s_waitcnt lgkmcnt(11)
	v_pk_fma_f32 v[190:191], v[60:61], v[140:141], v[190:191]
	v_pk_fma_f32 v[192:193], v[62:63], v[142:143], v[192:193]
	ds_read_b128 v[140:143], v184 offset:160
	s_waitcnt lgkmcnt(11)
	v_pk_fma_f32 v[190:191], v[44:45], v[144:145], v[190:191]
	v_pk_fma_f32 v[192:193], v[46:47], v[146:147], v[192:193]
	ds_read_b128 v[144:147], v184 offset:176
	s_waitcnt lgkmcnt(11)
	v_pk_mul_f32 v[194:195], v[28:29], v[148:149]
	v_pk_mul_f32 v[196:197], v[30:31], v[150:151]
	ds_read_b128 v[148:151], v184 offset:192
	s_waitcnt lgkmcnt(11)
	v_pk_fma_f32 v[194:195], v[8:9], v[152:153], v[194:195]
	v_pk_fma_f32 v[196:197], v[10:11], v[154:155], v[196:197]
	ds_read_b128 v[152:155], v184 offset:208
	s_waitcnt lgkmcnt(11)
	v_pk_fma_f32 v[194:195], v[4:5], v[156:157], v[194:195]
	v_pk_fma_f32 v[196:197], v[6:7], v[158:159], v[196:197]
	ds_read_b128 v[156:159], v184 offset:224
	s_waitcnt lgkmcnt(11)
	v_pk_fma_f32 v[194:195], v[0:1], v[160:161], v[194:195]
	v_pk_fma_f32 v[196:197], v[2:3], v[162:163], v[196:197]
	ds_read_b128 v[160:163], v184 offset:240
	s_waitcnt lgkmcnt(11)
	v_pk_fma_f32 v[194:195], v[24:25], v[116:117], v[194:195]
	v_pk_fma_f32 v[196:197], v[26:27], v[118:119], v[196:197]
	s_waitcnt lgkmcnt(10)
	v_pk_fma_f32 v[194:195], v[16:17], v[120:121], v[194:195]
	v_pk_fma_f32 v[196:197], v[18:19], v[122:123], v[196:197]
	s_waitcnt lgkmcnt(9)
	v_pk_fma_f32 v[194:195], v[20:21], v[124:125], v[194:195]
	v_pk_fma_f32 v[196:197], v[22:23], v[126:127], v[196:197]
	s_waitcnt lgkmcnt(8)
	v_pk_fma_f32 v[194:195], v[12:13], v[128:129], v[194:195]
	v_pk_fma_f32 v[196:197], v[14:15], v[130:131], v[196:197]
	s_waitcnt lgkmcnt(7)
	v_pk_fma_f32 v[194:195], v[48:49], v[132:133], v[194:195]
	v_pk_fma_f32 v[196:197], v[50:51], v[134:135], v[196:197]
	s_waitcnt lgkmcnt(6)
	v_pk_fma_f32 v[194:195], v[32:33], v[136:137], v[194:195]
	v_pk_fma_f32 v[196:197], v[34:35], v[138:139], v[196:197]
	s_waitcnt lgkmcnt(5)
	v_pk_fma_f32 v[194:195], v[52:53], v[140:141], v[194:195]
	v_pk_fma_f32 v[196:197], v[54:55], v[142:143], v[196:197]
	s_waitcnt lgkmcnt(4)
	v_pk_fma_f32 v[194:195], v[36:37], v[144:145], v[194:195]
	v_pk_fma_f32 v[196:197], v[38:39], v[146:147], v[196:197]
	s_waitcnt lgkmcnt(3)
	v_pk_fma_f32 v[194:195], v[56:57], v[148:149], v[194:195]
	v_pk_fma_f32 v[196:197], v[58:59], v[150:151], v[196:197]
	s_waitcnt lgkmcnt(2)
	v_pk_fma_f32 v[194:195], v[40:41], v[152:153], v[194:195]
	v_pk_fma_f32 v[196:197], v[42:43], v[154:155], v[196:197]
	s_waitcnt lgkmcnt(1)
	v_pk_fma_f32 v[194:195], v[60:61], v[156:157], v[194:195]
	v_pk_fma_f32 v[196:197], v[62:63], v[158:159], v[196:197]
	s_waitcnt lgkmcnt(0)
	v_pk_fma_f32 v[194:195], v[44:45], v[160:161], v[194:195]
	v_pk_fma_f32 v[196:197], v[46:47], v[162:163], v[196:197]
	v_add_f32_e32 v186, v186, v187
	v_add_f32_e32 v188, v188, v189
	v_add_f32_e32 v68, v186, v188
	v_add_f32_e32 v190, v190, v191
	v_add_f32_e32 v192, v192, v193
	v_add_f32_e32 v67, v190, v192
	v_add_f32_e32 v194, v194, v195
	v_add_f32_e32 v196, v196, v197
	v_add_f32_e32 v71, v194, v196
	v_fma_f32 v68, -v66, v69, v68
	v_fma_f32 v67, -v66, v70, v67
	s_mul_i32 s13, s10, 0x210
	s_add_i32 s16, s13, 0
	s_add_i32 s16, s16, 0x21420
	v_mov_b32_e32 v0, v71
	v_and_b32_e32 v3, 64, v237
	v_fmac_f32_e32 v0, 0x80000000, v66
	v_add_u32_e32 v3, 64, v3
	v_xor_b32_e32 v4, 1, v237
	v_cndmask_b32_e32 v2, v243, v0, vcc
	s_waitcnt vmcnt(0)
	v_mul_f32_e32 v0, 0x3fb8aa3b, v65
	v_cmp_lt_i32_e64 s[22:23], v4, v3
	v_max_f32_e32 v1, v2, v0
	v_max3_f32 v1, v68, v67, v1
	v_cndmask_b32_e64 v4, v237, v4, s[22:23]
	v_lshlrev_b32_e32 v5, 2, v4
	ds_bpermute_b32 v4, v5, v1
	s_waitcnt lgkmcnt(0)
	v_max_f32_e32 v4, v4, v4
	v_max_f32_e32 v1, v1, v4
	v_xor_b32_e32 v4, 2, v237
	v_cmp_lt_i32_e64 s[22:23], v4, v3
	s_nop 1
	v_cndmask_b32_e64 v4, v237, v4, s[22:23]
	v_lshlrev_b32_e32 v6, 2, v4
	ds_bpermute_b32 v4, v6, v1
	s_waitcnt lgkmcnt(0)
	v_max_f32_e32 v4, v4, v4
	v_max_f32_e32 v1, v1, v4
	v_xor_b32_e32 v4, 4, v237
	v_cmp_lt_i32_e64 s[22:23], v4, v3
	s_nop 1
	v_cndmask_b32_e64 v4, v237, v4, s[22:23]
	v_lshlrev_b32_e32 v7, 2, v4
	ds_bpermute_b32 v4, v7, v1
	s_waitcnt lgkmcnt(0)
	v_max_f32_e32 v4, v4, v4
	v_max_f32_e32 v1, v1, v4
	v_xor_b32_e32 v4, 8, v237
	v_cmp_lt_i32_e64 s[22:23], v4, v3
	s_nop 1
	v_cndmask_b32_e64 v4, v237, v4, s[22:23]
	v_lshlrev_b32_e32 v8, 2, v4
	ds_bpermute_b32 v4, v8, v1
	s_waitcnt lgkmcnt(0)
	v_max_f32_e32 v4, v4, v4
	v_max_f32_e32 v1, v1, v4
	v_xor_b32_e32 v4, 16, v237
	v_cmp_lt_i32_e64 s[22:23], v4, v3
	s_nop 1
	v_cndmask_b32_e64 v4, v237, v4, s[22:23]
	v_lshlrev_b32_e32 v9, 2, v4
	ds_bpermute_b32 v4, v9, v1
	s_waitcnt lgkmcnt(0)
	v_max_f32_e32 v4, v4, v4
	v_max_f32_e32 v1, v1, v4
	v_xor_b32_e32 v4, 32, v237
	v_cmp_lt_i32_e64 s[22:23], v4, v3
	s_nop 1
	v_cndmask_b32_e64 v3, v237, v4, s[22:23]
	v_lshlrev_b32_e32 v3, 2, v3
	ds_bpermute_b32 v4, v3, v1
	s_waitcnt lgkmcnt(0)
	v_max_f32_e32 v4, v4, v4
	v_max_f32_e32 v1, v1, v4
	v_sub_f32_e32 v4, v68, v1
	v_exp_f32_e32 v10, v4
	v_sub_f32_e32 v11, v67, v1
	v_exp_f32_e32 v11, v11
	v_sub_f32_e32 v2, v2, v1
	v_add_f32_e32 v4, 0, v10
	v_add_f32_e32 v12, v11, v4
	v_exp_f32_e32 v4, v2
	s_nop 0
	v_add_f32_e32 v2, v4, v12
	ds_bpermute_b32 v5, v5, v2
	s_waitcnt lgkmcnt(0)
	v_add_f32_e32 v2, v2, v5
	ds_bpermute_b32 v5, v6, v2
	s_waitcnt lgkmcnt(0)
	v_add_f32_e32 v2, v2, v5
	ds_bpermute_b32 v5, v7, v2
	s_waitcnt lgkmcnt(0)
	v_add_f32_e32 v2, v2, v5
	ds_bpermute_b32 v5, v8, v2
	s_waitcnt lgkmcnt(0)
	v_add_f32_e32 v2, v2, v5
	ds_bpermute_b32 v5, v9, v2
	s_waitcnt lgkmcnt(0)
	v_add_f32_e32 v2, v2, v5
	ds_bpermute_b32 v3, v3, v2
	v_lshl_add_u32 v5, v64, 2, s16
	ds_write2st64_b32 v5, v10, v11 offset1:1
	s_and_saveexec_b64 s[10:11], vcc
	v_mov_b32_e32 v5, s16
	ds_write_b32 v5, v4 offset:512
	s_or_b64 exec, exec, s[10:11]
	s_waitcnt lgkmcnt(0)
	s_add_i32 s10, s12, 0x10a10
	v_lshlrev_b32_e32 v149, 2, v64
	v_add_u32_e32 v149, s10, v149
	v_add_u32_e32 v150, 0x400, v149
	v_add_u32_e32 v151, 0x800, v149
	v_add_u32_e32 v152, 0xc00, v149
	s_add_i32 s11, s13, 0x21420
	v_mov_b32_e32 v148, s11
	v_mov_b32_e32 v4, 0
	ds_read_b128 v[116:119], v148
	ds_read_b128 v[120:123], v148 offset:16
	ds_read2_b32 v[124:125], v149 offset1:132
	ds_read2_b32 v[126:127], v150 offset0:8 offset1:140
	ds_read2_b32 v[128:129], v151 offset0:16 offset1:148
	ds_read2_b32 v[130:131], v152 offset0:24 offset1:156
	v_add_u32_e32 v149, 0x1080, v149
	v_add_u32_e32 v150, 0x1080, v150
	v_add_u32_e32 v151, 0x1080, v151
	v_add_u32_e32 v152, 0x1080, v152
	ds_read_b128 v[132:135], v148 offset:32
	ds_read_b128 v[136:139], v148 offset:48
	ds_read2_b32 v[140:141], v149 offset1:132
	ds_read2_b32 v[142:143], v150 offset0:8 offset1:140
	ds_read2_b32 v[144:145], v151 offset0:16 offset1:148
	ds_read2_b32 v[146:147], v152 offset0:24 offset1:156
	v_add_u32_e32 v149, 0x1080, v149
	v_add_u32_e32 v150, 0x1080, v150
	v_add_u32_e32 v151, 0x1080, v151
	v_add_u32_e32 v152, 0x1080, v152
	s_waitcnt lgkmcnt(6)
	v_fmac_f32_e32 v4, v116, v124
	v_fmac_f32_e32 v4, v117, v125
	v_fmac_f32_e32 v4, v118, v126
	v_fmac_f32_e32 v4, v119, v127
	v_fmac_f32_e32 v4, v120, v128
	v_fmac_f32_e32 v4, v121, v129
	v_fmac_f32_e32 v4, v122, v130
	v_fmac_f32_e32 v4, v123, v131
	ds_read_b128 v[116:119], v148 offset:64
	ds_read_b128 v[120:123], v148 offset:80
	ds_read2_b32 v[124:125], v149 offset1:132
	ds_read2_b32 v[126:127], v150 offset0:8 offset1:140
	ds_read2_b32 v[128:129], v151 offset0:16 offset1:148
	ds_read2_b32 v[130:131], v152 offset0:24 offset1:156
	v_add_u32_e32 v149, 0x1080, v149
	v_add_u32_e32 v150, 0x1080, v150
	v_add_u32_e32 v151, 0x1080, v151
	v_add_u32_e32 v152, 0x1080, v152
	s_waitcnt lgkmcnt(6)
	v_fmac_f32_e32 v4, v132, v140
	v_fmac_f32_e32 v4, v133, v141
	v_fmac_f32_e32 v4, v134, v142
	v_fmac_f32_e32 v4, v135, v143
	v_fmac_f32_e32 v4, v136, v144
	v_fmac_f32_e32 v4, v137, v145
	v_fmac_f32_e32 v4, v138, v146
	v_fmac_f32_e32 v4, v139, v147
	ds_read_b128 v[132:135], v148 offset:96
	ds_read_b128 v[136:139], v148 offset:112
	ds_read2_b32 v[140:141], v149 offset1:132
	ds_read2_b32 v[142:143], v150 offset0:8 offset1:140
	ds_read2_b32 v[144:145], v151 offset0:16 offset1:148
	ds_read2_b32 v[146:147], v152 offset0:24 offset1:156
	v_add_u32_e32 v149, 0x1080, v149
	v_add_u32_e32 v150, 0x1080, v150
	v_add_u32_e32 v151, 0x1080, v151
	v_add_u32_e32 v152, 0x1080, v152
	s_waitcnt lgkmcnt(6)
	v_fmac_f32_e32 v4, v116, v124
	v_fmac_f32_e32 v4, v117, v125
	v_fmac_f32_e32 v4, v118, v126
	v_fmac_f32_e32 v4, v119, v127
	v_fmac_f32_e32 v4, v120, v128
	v_fmac_f32_e32 v4, v121, v129
	v_fmac_f32_e32 v4, v122, v130
	v_fmac_f32_e32 v4, v123, v131
	ds_read_b128 v[116:119], v148 offset:128
	ds_read_b128 v[120:123], v148 offset:144
	ds_read2_b32 v[124:125], v149 offset1:132
	ds_read2_b32 v[126:127], v150 offset0:8 offset1:140
	ds_read2_b32 v[128:129], v151 offset0:16 offset1:148
	ds_read2_b32 v[130:131], v152 offset0:24 offset1:156
	v_add_u32_e32 v149, 0x1080, v149
	v_add_u32_e32 v150, 0x1080, v150
	v_add_u32_e32 v151, 0x1080, v151
	v_add_u32_e32 v152, 0x1080, v152
	s_waitcnt lgkmcnt(6)
	v_fmac_f32_e32 v4, v132, v140
	v_fmac_f32_e32 v4, v133, v141
	v_fmac_f32_e32 v4, v134, v142
	v_fmac_f32_e32 v4, v135, v143
	v_fmac_f32_e32 v4, v136, v144
	v_fmac_f32_e32 v4, v137, v145
	v_fmac_f32_e32 v4, v138, v146
	v_fmac_f32_e32 v4, v139, v147
	ds_read_b128 v[132:135], v148 offset:160
	ds_read_b128 v[136:139], v148 offset:176
	ds_read2_b32 v[140:141], v149 offset1:132
	ds_read2_b32 v[142:143], v150 offset0:8 offset1:140
	ds_read2_b32 v[144:145], v151 offset0:16 offset1:148
	ds_read2_b32 v[146:147], v152 offset0:24 offset1:156
	v_add_u32_e32 v149, 0x1080, v149
	v_add_u32_e32 v150, 0x1080, v150
	v_add_u32_e32 v151, 0x1080, v151
	v_add_u32_e32 v152, 0x1080, v152
	s_waitcnt lgkmcnt(6)
	v_fmac_f32_e32 v4, v116, v124
	v_fmac_f32_e32 v4, v117, v125
	v_fmac_f32_e32 v4, v118, v126
	v_fmac_f32_e32 v4, v119, v127
	v_fmac_f32_e32 v4, v120, v128
	v_fmac_f32_e32 v4, v121, v129
	v_fmac_f32_e32 v4, v122, v130
	v_fmac_f32_e32 v4, v123, v131
	ds_read_b128 v[116:119], v148 offset:192
	ds_read_b128 v[120:123], v148 offset:208
	ds_read2_b32 v[124:125], v149 offset1:132
	ds_read2_b32 v[126:127], v150 offset0:8 offset1:140
	ds_read2_b32 v[128:129], v151 offset0:16 offset1:148
	ds_read2_b32 v[130:131], v152 offset0:24 offset1:156
	v_add_u32_e32 v149, 0x1080, v149
	v_add_u32_e32 v150, 0x1080, v150
	v_add_u32_e32 v151, 0x1080, v151
	v_add_u32_e32 v152, 0x1080, v152
	s_waitcnt lgkmcnt(6)
	v_fmac_f32_e32 v4, v132, v140
	v_fmac_f32_e32 v4, v133, v141
	v_fmac_f32_e32 v4, v134, v142
	v_fmac_f32_e32 v4, v135, v143
	v_fmac_f32_e32 v4, v136, v144
	v_fmac_f32_e32 v4, v137, v145
	v_fmac_f32_e32 v4, v138, v146
	v_fmac_f32_e32 v4, v139, v147
	ds_read_b128 v[132:135], v148 offset:224
	ds_read_b128 v[136:139], v148 offset:240
	ds_read2_b32 v[140:141], v149 offset1:132
	ds_read2_b32 v[142:143], v150 offset0:8 offset1:140
	ds_read2_b32 v[144:145], v151 offset0:16 offset1:148
	ds_read2_b32 v[146:147], v152 offset0:24 offset1:156
	v_add_u32_e32 v149, 0x1080, v149
	v_add_u32_e32 v150, 0x1080, v150
	v_add_u32_e32 v151, 0x1080, v151
	v_add_u32_e32 v152, 0x1080, v152
	s_waitcnt lgkmcnt(6)
	v_fmac_f32_e32 v4, v116, v124
	v_fmac_f32_e32 v4, v117, v125
	v_fmac_f32_e32 v4, v118, v126
	v_fmac_f32_e32 v4, v119, v127
	v_fmac_f32_e32 v4, v120, v128
	v_fmac_f32_e32 v4, v121, v129
	v_fmac_f32_e32 v4, v122, v130
	v_fmac_f32_e32 v4, v123, v131
	ds_read_b128 v[116:119], v148 offset:256
	ds_read_b128 v[120:123], v148 offset:272
	ds_read2_b32 v[124:125], v149 offset1:132
	ds_read2_b32 v[126:127], v150 offset0:8 offset1:140
	ds_read2_b32 v[128:129], v151 offset0:16 offset1:148
	ds_read2_b32 v[130:131], v152 offset0:24 offset1:156
	v_add_u32_e32 v149, 0x1080, v149
	v_add_u32_e32 v150, 0x1080, v150
	v_add_u32_e32 v151, 0x1080, v151
	v_add_u32_e32 v152, 0x1080, v152
	s_waitcnt lgkmcnt(6)
	v_fmac_f32_e32 v4, v132, v140
	v_fmac_f32_e32 v4, v133, v141
	v_fmac_f32_e32 v4, v134, v142
	v_fmac_f32_e32 v4, v135, v143
	v_fmac_f32_e32 v4, v136, v144
	v_fmac_f32_e32 v4, v137, v145
	v_fmac_f32_e32 v4, v138, v146
	v_fmac_f32_e32 v4, v139, v147
	ds_read_b128 v[132:135], v148 offset:288
	ds_read_b128 v[136:139], v148 offset:304
	ds_read2_b32 v[140:141], v149 offset1:132
	ds_read2_b32 v[142:143], v150 offset0:8 offset1:140
	ds_read2_b32 v[144:145], v151 offset0:16 offset1:148
	ds_read2_b32 v[146:147], v152 offset0:24 offset1:156
	v_add_u32_e32 v149, 0x1080, v149
	v_add_u32_e32 v150, 0x1080, v150
	v_add_u32_e32 v151, 0x1080, v151
	v_add_u32_e32 v152, 0x1080, v152
	s_waitcnt lgkmcnt(6)
	v_fmac_f32_e32 v4, v116, v124
	v_fmac_f32_e32 v4, v117, v125
	v_fmac_f32_e32 v4, v118, v126
	v_fmac_f32_e32 v4, v119, v127
	v_fmac_f32_e32 v4, v120, v128
	v_fmac_f32_e32 v4, v121, v129
	v_fmac_f32_e32 v4, v122, v130
	v_fmac_f32_e32 v4, v123, v131
	ds_read_b128 v[116:119], v148 offset:320
	ds_read_b128 v[120:123], v148 offset:336
	ds_read2_b32 v[124:125], v149 offset1:132
	ds_read2_b32 v[126:127], v150 offset0:8 offset1:140
	ds_read2_b32 v[128:129], v151 offset0:16 offset1:148
	ds_read2_b32 v[130:131], v152 offset0:24 offset1:156
	v_add_u32_e32 v149, 0x1080, v149
	v_add_u32_e32 v150, 0x1080, v150
	v_add_u32_e32 v151, 0x1080, v151
	v_add_u32_e32 v152, 0x1080, v152
	s_waitcnt lgkmcnt(6)
	v_fmac_f32_e32 v4, v132, v140
	v_fmac_f32_e32 v4, v133, v141
	v_fmac_f32_e32 v4, v134, v142
	v_fmac_f32_e32 v4, v135, v143
	v_fmac_f32_e32 v4, v136, v144
	v_fmac_f32_e32 v4, v137, v145
	v_fmac_f32_e32 v4, v138, v146
	v_fmac_f32_e32 v4, v139, v147
	ds_read_b128 v[132:135], v148 offset:352
	ds_read_b128 v[136:139], v148 offset:368
	ds_read2_b32 v[140:141], v149 offset1:132
	ds_read2_b32 v[142:143], v150 offset0:8 offset1:140
	ds_read2_b32 v[144:145], v151 offset0:16 offset1:148
	ds_read2_b32 v[146:147], v152 offset0:24 offset1:156
	v_add_u32_e32 v149, 0x1080, v149
	v_add_u32_e32 v150, 0x1080, v150
	v_add_u32_e32 v151, 0x1080, v151
	v_add_u32_e32 v152, 0x1080, v152
	s_waitcnt lgkmcnt(6)
	v_fmac_f32_e32 v4, v116, v124
	v_fmac_f32_e32 v4, v117, v125
	v_fmac_f32_e32 v4, v118, v126
	v_fmac_f32_e32 v4, v119, v127
	v_fmac_f32_e32 v4, v120, v128
	v_fmac_f32_e32 v4, v121, v129
	v_fmac_f32_e32 v4, v122, v130
	v_fmac_f32_e32 v4, v123, v131
	ds_read_b128 v[116:119], v148 offset:384
	ds_read_b128 v[120:123], v148 offset:400
	ds_read2_b32 v[124:125], v149 offset1:132
	ds_read2_b32 v[126:127], v150 offset0:8 offset1:140
	ds_read2_b32 v[128:129], v151 offset0:16 offset1:148
	ds_read2_b32 v[130:131], v152 offset0:24 offset1:156
	v_add_u32_e32 v149, 0x1080, v149
	v_add_u32_e32 v150, 0x1080, v150
	v_add_u32_e32 v151, 0x1080, v151
	v_add_u32_e32 v152, 0x1080, v152
	s_waitcnt lgkmcnt(6)
	v_fmac_f32_e32 v4, v132, v140
	v_fmac_f32_e32 v4, v133, v141
	v_fmac_f32_e32 v4, v134, v142
	v_fmac_f32_e32 v4, v135, v143
	v_fmac_f32_e32 v4, v136, v144
	v_fmac_f32_e32 v4, v137, v145
	v_fmac_f32_e32 v4, v138, v146
	v_fmac_f32_e32 v4, v139, v147
	ds_read_b128 v[132:135], v148 offset:416
	ds_read_b128 v[136:139], v148 offset:432
	ds_read2_b32 v[140:141], v149 offset1:132
	ds_read2_b32 v[142:143], v150 offset0:8 offset1:140
	ds_read2_b32 v[144:145], v151 offset0:16 offset1:148
	ds_read2_b32 v[146:147], v152 offset0:24 offset1:156
	v_add_u32_e32 v149, 0x1080, v149
	v_add_u32_e32 v150, 0x1080, v150
	v_add_u32_e32 v151, 0x1080, v151
	v_add_u32_e32 v152, 0x1080, v152
	s_waitcnt lgkmcnt(6)
	v_fmac_f32_e32 v4, v116, v124
	v_fmac_f32_e32 v4, v117, v125
	v_fmac_f32_e32 v4, v118, v126
	v_fmac_f32_e32 v4, v119, v127
	v_fmac_f32_e32 v4, v120, v128
	v_fmac_f32_e32 v4, v121, v129
	v_fmac_f32_e32 v4, v122, v130
	v_fmac_f32_e32 v4, v123, v131
	ds_read_b128 v[116:119], v148 offset:448
	ds_read_b128 v[120:123], v148 offset:464
	ds_read2_b32 v[124:125], v149 offset1:132
	ds_read2_b32 v[126:127], v150 offset0:8 offset1:140
	ds_read2_b32 v[128:129], v151 offset0:16 offset1:148
	ds_read2_b32 v[130:131], v152 offset0:24 offset1:156
	v_add_u32_e32 v149, 0x1080, v149
	v_add_u32_e32 v150, 0x1080, v150
	v_add_u32_e32 v151, 0x1080, v151
	v_add_u32_e32 v152, 0x1080, v152
	s_waitcnt lgkmcnt(6)
	v_fmac_f32_e32 v4, v132, v140
	v_fmac_f32_e32 v4, v133, v141
	v_fmac_f32_e32 v4, v134, v142
	v_fmac_f32_e32 v4, v135, v143
	v_fmac_f32_e32 v4, v136, v144
	v_fmac_f32_e32 v4, v137, v145
	v_fmac_f32_e32 v4, v138, v146
	v_fmac_f32_e32 v4, v139, v147
	ds_read_b128 v[132:135], v148 offset:480
	ds_read_b128 v[136:139], v148 offset:496
	ds_read2_b32 v[140:141], v149 offset1:132
	ds_read2_b32 v[142:143], v150 offset0:8 offset1:140
	ds_read2_b32 v[144:145], v151 offset0:16 offset1:148
	ds_read2_b32 v[146:147], v152 offset0:24 offset1:156
	v_add_u32_e32 v149, 0x1080, v149
	v_add_u32_e32 v150, 0x1080, v150
	v_add_u32_e32 v151, 0x1080, v151
	v_add_u32_e32 v152, 0x1080, v152
	s_waitcnt lgkmcnt(6)
	v_fmac_f32_e32 v4, v116, v124
	v_fmac_f32_e32 v4, v117, v125
	v_fmac_f32_e32 v4, v118, v126
	v_fmac_f32_e32 v4, v119, v127
	v_fmac_f32_e32 v4, v120, v128
	v_fmac_f32_e32 v4, v121, v129
	v_fmac_f32_e32 v4, v122, v130
	v_fmac_f32_e32 v4, v123, v131
	ds_read_b32 v153, v148 offset:512
	ds_read_b32 v154, v149
	s_waitcnt lgkmcnt(2)
	v_fmac_f32_e32 v4, v132, v140
	v_fmac_f32_e32 v4, v133, v141
	v_fmac_f32_e32 v4, v134, v142
	v_fmac_f32_e32 v4, v135, v143
	v_fmac_f32_e32 v4, v136, v144
	v_fmac_f32_e32 v4, v137, v145
	v_fmac_f32_e32 v4, v138, v146
	v_fmac_f32_e32 v4, v139, v147
	s_waitcnt lgkmcnt(0)
	v_fmac_f32_e32 v4, v153, v154
